# attention loops: O and l rescale executed inside the rare reference-update path; common path adds the row sum without computing or testing alpha
# baseline (speedup 1.0000x reference)
; __device__ __forceinline__ float max_x32(float v) { const unsigned u = __float_as_uint(v); auto r = __builtin_amdgcn_permlane32_swap(u, u, false, false); return fmaxf(__uint_as_float(r[0]), __uint_as_float(r[1])); }
; template <bool MASKED>
; __device__ __forceinline__ void softmax_tile(f32x16& s0, f32x16& s1, float& m, float& l, float& alpha, unsigned mlo, unsigned mhi, bf16x8 (&pk)[4]) {
;     ...
;     float mx = fmaxf(s0[0], s1[0]);
; #pragma unroll
;     for (int r = 1; r < 16; ++r) mx = fmaxf(mx, fmaxf(s0[r], s1[r]));
;     mx = max_x32(mx);
;     const float mn = fmaxf(m, mx);
;     alpha = __builtin_amdgcn_exp2f(m - mn); m = mn;
;     float sum = 0.f;
; #pragma unroll
;     for (int r = 0; r < 16; ++r) {
;         float p0 = __builtin_amdgcn_exp2f(s0[r] - mn), p1 = __builtin_amdgcn_exp2f(s1[r] - mn);
;         if (MASKED) { if (s0[r] <= -1e29f) p0 = 0.f; if (s1[r] <= -1e29f) p1 = 0.f; }
;         s0[r] = p0; s1[r] = p1; sum += p0 + p1;
;     }
;     l = l * alpha + sum;
.LBB0_626:
	s_cmp_gt_i32 s7, s25
	s_cbranch_scc1 .LBB0_630
	s_mul_i32 s26, s17, 0xa000
	s_add_i32 s26, s26, 0
	v_add_u32_e32 v0, s26, v124
	v_add_u32_e32 v70, v0, v126
	v_add_u32_e32 v74, v0, v127
	ds_read_b128 v[66:69], v70
	ds_read_b128 v[70:73], v70 offset:8192
	ds_read_b128 v[150:153], v74
	ds_read_b128 v[154:157], v74 offset:8192
	v_add_u32_e32 v74, v0, v128
	v_add_u32_e32 v0, v0, v129
	ds_read_b128 v[158:161], v74
	ds_read_b128 v[162:165], v74 offset:8192
	ds_read_b128 v[166:169], v0
	ds_read_b128 v[170:173], v0 offset:8192
	s_waitcnt lgkmcnt(0)
	v_mfma_f32_32x32x16_bf16 v[82:97], v[66:69], v[98:101], v[236:251]
	v_mfma_f32_32x32x16_bf16 v[66:81], v[70:73], v[98:101], v[236:251]
	v_mfma_f32_32x32x16_bf16 v[82:97], v[150:153], v[102:105], v[82:97]
	v_mfma_f32_32x32x16_bf16 v[66:81], v[154:157], v[102:105], v[66:81]
	v_mfma_f32_32x32x16_bf16 v[82:97], v[158:161], v[106:109], v[82:97]
	v_mfma_f32_32x32x16_bf16 v[66:81], v[162:165], v[106:109], v[66:81]
	v_mfma_f32_32x32x16_bf16 v[82:97], v[166:169], v[110:113], v[82:97]
	v_mfma_f32_32x32x16_bf16 v[66:81], v[170:173], v[110:113], v[66:81]
	s_nop 11
	v_max3_f32 v150, v82, v83, v84
	v_max3_f32 v151, v85, v86, v87
	v_max3_f32 v152, v88, v89, v90
	v_max3_f32 v153, v91, v92, v93
	v_max3_f32 v154, v94, v95, v96
	v_max3_f32 v155, v97, v66, v67
	v_max3_f32 v156, v68, v69, v70
	v_max3_f32 v157, v71, v72, v73
	v_max3_f32 v158, v74, v75, v76
	v_max3_f32 v159, v77, v78, v79
	v_max3_f32 v150, v150, v151, v152
	v_max3_f32 v153, v153, v154, v155
	v_max3_f32 v156, v156, v157, v158
	v_max3_f32 v159, v159, v80, v81
	v_max3_f32 v150, v150, v153, v156
	v_max_f32_e32 v150, v150, v159
	v_mov_b32_e32 v151, v150
	s_nop 1
	v_permlane32_swap_b32_e32 v150, v151
	v_max_f32_e32 v150, v150, v151
	v_mov_b32_e32 v146, v148
	v_cmp_lt_f32_e32 vcc, v253, v150
	s_cbranch_vccz .Lm2_cfast
	v_add_f32_e32 v151, v150, v252
	v_cndmask_b32_e32 v146, v148, v151, vcc
	v_sub_f32_e32 v151, v146, v252
	v_cndmask_b32_e32 v151, 0, v151, vcc
	v_mov_b32_e32 v150, 0x41000000
	v_cndmask_b32_e32 v253, v253, v150, vcc
	v_cndmask_b32_e32 v252, v252, v146, vcc
	v_sub_f32_e32 v0, v148, v146
	v_exp_f32_e32 v0, v0
	v_sub_f32_e32 v82, v82, v151
	v_sub_f32_e32 v83, v83, v151
	v_sub_f32_e32 v84, v84, v151
	v_sub_f32_e32 v85, v85, v151
	v_sub_f32_e32 v86, v86, v151
	v_sub_f32_e32 v87, v87, v151
	v_sub_f32_e32 v88, v88, v151
	v_sub_f32_e32 v89, v89, v151
	v_sub_f32_e32 v90, v90, v151
	v_sub_f32_e32 v91, v91, v151
	v_sub_f32_e32 v92, v92, v151
	v_sub_f32_e32 v93, v93, v151
	v_sub_f32_e32 v94, v94, v151
	v_sub_f32_e32 v95, v95, v151
	v_sub_f32_e32 v96, v96, v151
	v_sub_f32_e32 v97, v97, v151
	v_sub_f32_e32 v66, v66, v151
	v_sub_f32_e32 v67, v67, v151
	v_sub_f32_e32 v68, v68, v151
	v_sub_f32_e32 v69, v69, v151
	v_sub_f32_e32 v70, v70, v151
	v_sub_f32_e32 v71, v71, v151
	v_sub_f32_e32 v72, v72, v151
	v_sub_f32_e32 v73, v73, v151
	v_sub_f32_e32 v74, v74, v151
	v_sub_f32_e32 v75, v75, v151
	v_sub_f32_e32 v76, v76, v151
	v_sub_f32_e32 v77, v77, v151
	v_sub_f32_e32 v78, v78, v151
	v_sub_f32_e32 v79, v79, v151
	v_sub_f32_e32 v80, v80, v151
	v_sub_f32_e32 v81, v81, v151
	v_sub_f32_e32 v236, 0, v252
	v_sub_f32_e32 v237, 0, v252
	v_sub_f32_e32 v238, 0, v252
	v_sub_f32_e32 v239, 0, v252
	v_sub_f32_e32 v240, 0, v252
	v_sub_f32_e32 v241, 0, v252
	v_sub_f32_e32 v242, 0, v252
	v_sub_f32_e32 v243, 0, v252
	v_sub_f32_e32 v244, 0, v252
	v_sub_f32_e32 v245, 0, v252
	v_sub_f32_e32 v246, 0, v252
	v_sub_f32_e32 v247, 0, v252
	v_sub_f32_e32 v248, 0, v252
	v_sub_f32_e32 v249, 0, v252
	v_sub_f32_e32 v250, 0, v252
	v_sub_f32_e32 v251, 0, v252
	v_mul_f32_e32 v147, v147, v0
	v_pk_mul_f32 v[64:65], v[64:65], v[0:1] op_sel_hi:[1,0]
	v_pk_mul_f32 v[62:63], v[62:63], v[0:1] op_sel_hi:[1,0]
	v_pk_mul_f32 v[60:61], v[60:61], v[0:1] op_sel_hi:[1,0]
	v_pk_mul_f32 v[58:59], v[58:59], v[0:1] op_sel_hi:[1,0]
	v_pk_mul_f32 v[56:57], v[56:57], v[0:1] op_sel_hi:[1,0]
	v_pk_mul_f32 v[54:55], v[54:55], v[0:1] op_sel_hi:[1,0]
	v_pk_mul_f32 v[52:53], v[52:53], v[0:1] op_sel_hi:[1,0]
	v_pk_mul_f32 v[50:51], v[50:51], v[0:1] op_sel_hi:[1,0]
	v_pk_mul_f32 v[48:49], v[48:49], v[0:1] op_sel_hi:[1,0]
	v_pk_mul_f32 v[46:47], v[46:47], v[0:1] op_sel_hi:[1,0]
	v_pk_mul_f32 v[44:45], v[44:45], v[0:1] op_sel_hi:[1,0]
	v_pk_mul_f32 v[42:43], v[42:43], v[0:1] op_sel_hi:[1,0]
	v_pk_mul_f32 v[40:41], v[40:41], v[0:1] op_sel_hi:[1,0]
	v_pk_mul_f32 v[38:39], v[38:39], v[0:1] op_sel_hi:[1,0]
	v_pk_mul_f32 v[36:37], v[36:37], v[0:1] op_sel_hi:[1,0]
	v_pk_mul_f32 v[34:35], v[34:35], v[0:1] op_sel_hi:[1,0]
	v_pk_mul_f32 v[32:33], v[32:33], v[0:1] op_sel_hi:[1,0]
	v_pk_mul_f32 v[30:31], v[30:31], v[0:1] op_sel_hi:[1,0]
	v_pk_mul_f32 v[28:29], v[28:29], v[0:1] op_sel_hi:[1,0]
	v_pk_mul_f32 v[26:27], v[26:27], v[0:1] op_sel_hi:[1,0]
	v_pk_mul_f32 v[24:25], v[24:25], v[0:1] op_sel_hi:[1,0]
	v_pk_mul_f32 v[22:23], v[22:23], v[0:1] op_sel_hi:[1,0]
	v_pk_mul_f32 v[20:21], v[20:21], v[0:1] op_sel_hi:[1,0]
	v_pk_mul_f32 v[18:19], v[18:19], v[0:1] op_sel_hi:[1,0]
	v_pk_mul_f32 v[16:17], v[16:17], v[0:1] op_sel_hi:[1,0]
	v_pk_mul_f32 v[14:15], v[14:15], v[0:1] op_sel_hi:[1,0]
	v_pk_mul_f32 v[12:13], v[12:13], v[0:1] op_sel_hi:[1,0]
	v_pk_mul_f32 v[10:11], v[10:11], v[0:1] op_sel_hi:[1,0]
	v_pk_mul_f32 v[8:9], v[8:9], v[0:1] op_sel_hi:[1,0]
	v_pk_mul_f32 v[6:7], v[6:7], v[0:1] op_sel_hi:[1,0]
	v_pk_mul_f32 v[4:5], v[4:5], v[0:1] op_sel_hi:[1,0]
	v_pk_mul_f32 v[2:3], v[2:3], v[0:1] op_sel_hi:[1,0]
; __device__ __forceinline__ unsigned cvtpk(float lo, float hi) { unsigned r; asm("v_cvt_pk_bf16_f32 %0, %1, %2" : "=v"(r) : "v"(lo), "v"(hi)); return r; }
; template <bool MASKED>
; __device__ __forceinline__ void softmax_tile(f32x16& s0, f32x16& s1, float& m, float& l, float& alpha, unsigned mlo, unsigned mhi, bf16x8 (&pk)[4]) {
;     ...
;     float sum = 0.f;
; #pragma unroll
;     for (int r = 0; r < 16; ++r) {
;         float p0 = __builtin_amdgcn_exp2f(s0[r] - mn), p1 = __builtin_amdgcn_exp2f(s1[r] - mn);
;         if (MASKED) { if (s0[r] <= -1e29f) p0 = 0.f; if (s1[r] <= -1e29f) p1 = 0.f; }
;         s0[r] = p0; s1[r] = p1; sum += p0 + p1;
;     }
;     l = l * alpha + sum;
; #pragma unroll
;     for (int k2 = 0; k2 < 2; ++k2) {
;         u32x4 a, b;
;         a.x = cvtpk(s0[8 * k2 + 0], s0[8 * k2 + 1]); a.y = cvtpk(s0[8 * k2 + 2], s0[8 * k2 + 3]); a.z = cvtpk(s0[8 * k2 + 4], s0[8 * k2 + 5]); a.w = cvtpk(s0[8 * k2 + 6], s0[8 * k2 + 7]);
;         b.x = cvtpk(s1[8 * k2 + 0], s1[8 * k2 + 1]); b.y = cvtpk(s1[8 * k2 + 2], s1[8 * k2 + 3]); b.z = cvtpk(s1[8 * k2 + 4], s1[8 * k2 + 5]); b.w = cvtpk(s1[8 * k2 + 6], s1[8 * k2 + 7]);
;         pk[k2] = __builtin_bit_cast(bf16x8, a); pk[2 + k2] = __builtin_bit_cast(bf16x8, b);
;     }
.Lm2_cfast:
	v_exp_f32_e32 v82, v82
	v_exp_f32_e32 v83, v83
	v_exp_f32_e32 v84, v84
	v_exp_f32_e32 v85, v85
	v_exp_f32_e32 v86, v86
	v_exp_f32_e32 v87, v87
	v_exp_f32_e32 v88, v88
	v_exp_f32_e32 v89, v89
	v_exp_f32_e32 v90, v90
	v_exp_f32_e32 v91, v91
	v_exp_f32_e32 v92, v92
	v_exp_f32_e32 v93, v93
	v_exp_f32_e32 v94, v94
	v_exp_f32_e32 v95, v95
	v_exp_f32_e32 v96, v96
	v_exp_f32_e32 v97, v97
	v_exp_f32_e32 v66, v66
	v_exp_f32_e32 v67, v67
	v_exp_f32_e32 v68, v68
	v_exp_f32_e32 v69, v69
	v_exp_f32_e32 v70, v70
	v_exp_f32_e32 v71, v71
	v_exp_f32_e32 v72, v72
	v_exp_f32_e32 v73, v73
	v_exp_f32_e32 v74, v74
	v_exp_f32_e32 v75, v75
	v_exp_f32_e32 v76, v76
	v_exp_f32_e32 v77, v77
	v_exp_f32_e32 v78, v78
	v_exp_f32_e32 v79, v79
	v_exp_f32_e32 v80, v80
	v_exp_f32_e32 v81, v81
	v_pk_add_f32 v[150:151], v[82:83], v[84:85]
	v_pk_add_f32 v[152:153], v[86:87], v[88:89]
	v_pk_add_f32 v[154:155], v[90:91], v[92:93]
	v_pk_add_f32 v[156:157], v[94:95], v[96:97]
	v_pk_add_f32 v[158:159], v[66:67], v[68:69]
	v_pk_add_f32 v[160:161], v[70:71], v[72:73]
	v_pk_add_f32 v[162:163], v[74:75], v[76:77]
	v_pk_add_f32 v[164:165], v[78:79], v[80:81]
	v_pk_add_f32 v[150:151], v[150:151], v[152:153]
	v_pk_add_f32 v[154:155], v[154:155], v[156:157]
	v_pk_add_f32 v[158:159], v[158:159], v[160:161]
	v_pk_add_f32 v[162:163], v[162:163], v[164:165]
	v_pk_add_f32 v[150:151], v[150:151], v[154:155]
	v_pk_add_f32 v[158:159], v[158:159], v[162:163]
	v_pk_add_f32 v[150:151], v[150:151], v[158:159]
	v_add_f32_e32 v164, v150, v151
	v_cvt_pk_bf16_f32 v66, v66, v67
	v_cvt_pk_bf16_f32 v67, v68, v69
	v_cvt_pk_bf16_f32 v68, v70, v71
	v_cvt_pk_bf16_f32 v69, v72, v73
	v_cvt_pk_bf16_f32 v70, v74, v75
	v_cvt_pk_bf16_f32 v71, v76, v77
	v_cvt_pk_bf16_f32 v72, v78, v79
	v_cvt_pk_bf16_f32 v73, v80, v81
	v_cvt_pk_bf16_f32 v74, v82, v83
	v_cvt_pk_bf16_f32 v75, v84, v85
	v_cvt_pk_bf16_f32 v76, v86, v87
	v_cvt_pk_bf16_f32 v77, v88, v89
	v_cvt_pk_bf16_f32 v78, v90, v91
	v_cvt_pk_bf16_f32 v79, v92, v93
	v_cvt_pk_bf16_f32 v80, v94, v95
	v_cvt_pk_bf16_f32 v81, v96, v97
	v_add_f32_e32 v164, v164, v147

; __device__ __forceinline__ float max_x32(float v) { const unsigned u = __float_as_uint(v); auto r = __builtin_amdgcn_permlane32_swap(u, u, false, false); return fmaxf(__uint_as_float(r[0]), __uint_as_float(r[1])); }
; template <bool MASKED>
; __device__ __forceinline__ void softmax_tile(f32x16& s0, f32x16& s1, float& m, float& l, float& alpha, unsigned mlo, unsigned mhi, bf16x8 (&pk)[4]) {
;     ...
;     if (MASKED) {
; #pragma unroll
;         for (int r = 0; r < 16; ++r) { const int bit = (r & 3) + 8 * (r >> 2); if (!((mlo >> bit) & 1u)) s0[r] = NEG; if (!((mhi >> bit) & 1u)) s1[r] = NEG; }
;     }
;     float mx = fmaxf(s0[0], s1[0]);
; #pragma unroll
;     for (int r = 1; r < 16; ++r) mx = fmaxf(mx, fmaxf(s0[r], s1[r]));
;     mx = max_x32(mx);
;     const float mn = fmaxf(m, mx);
;     alpha = __builtin_amdgcn_exp2f(m - mn); m = mn;
.LBB0_1176:
	s_andn2_b64 vcc, exec, s[12:13]
	s_cbranch_vccnz .LBB0_1180
	s_mul_i32 s12, s17, 0xa000
	s_add_i32 s12, s12, 0
	v_add_u32_e32 v194, s12, v141
	v_add_u32_e32 v70, v194, v143
	v_add_u32_e32 v74, v194, v144
	ds_read_b128 v[66:69], v70
	ds_read_b128 v[70:73], v70 offset:8192
	ds_read_b128 v[160:163], v74
	ds_read_b128 v[164:167], v74 offset:8192
	v_add_u32_e32 v74, v194, v145
	ds_read_b128 v[168:171], v74
	ds_read_b128 v[172:175], v74 offset:8192
	v_add_u32_e32 v74, v194, v146
	ds_read_b128 v[186:189], v74 offset:8192
	ds_read_b128 v[190:193], v74
	s_waitcnt lgkmcnt(0)
	v_mfma_f32_32x32x16_bf16 v[82:97], v[66:69], v[98:101], v[236:251]
	v_mfma_f32_32x32x16_bf16 v[66:81], v[70:73], v[98:101], v[236:251]
	v_mfma_f32_32x32x16_bf16 v[82:97], v[160:163], v[102:105], v[82:97]
	v_mfma_f32_32x32x16_bf16 v[66:81], v[164:167], v[102:105], v[66:81]
	v_mfma_f32_32x32x16_bf16 v[82:97], v[168:171], v[106:109], v[82:97]
	v_mfma_f32_32x32x16_bf16 v[66:81], v[172:175], v[106:109], v[66:81]
	v_mfma_f32_32x32x16_bf16 v[82:97], v[190:193], v[110:113], v[82:97]
	v_mfma_f32_32x32x16_bf16 v[66:81], v[186:189], v[110:113], v[66:81]
	v_add_u32_e32 v164, v194, v147
	v_add_u32_e32 v172, v194, v148
	v_add_u32_e32 v190, v194, v149
	v_add_u32_e32 v198, v194, v150
	ds_read_b128 v[160:163], v164
	ds_read_b128 v[164:167], v164 offset:8192
	ds_read_b128 v[168:171], v172
	ds_read_b128 v[172:175], v172 offset:8192
	ds_read_b128 v[186:189], v190
	ds_read_b128 v[190:193], v190 offset:8192
	ds_read_b128 v[194:197], v198 offset:8192
	ds_read_b128 v[206:209], v198
	s_waitcnt lgkmcnt(0)
	v_mfma_f32_32x32x16_bf16 v[82:97], v[160:163], v[114:117], v[82:97]
	v_mfma_f32_32x32x16_bf16 v[66:81], v[164:167], v[114:117], v[66:81]
	v_mfma_f32_32x32x16_bf16 v[82:97], v[168:171], v[118:121], v[82:97]
	v_mfma_f32_32x32x16_bf16 v[66:81], v[172:175], v[118:121], v[66:81]
	v_mfma_f32_32x32x16_bf16 v[82:97], v[186:189], v[122:125], v[82:97]
	v_mfma_f32_32x32x16_bf16 v[66:81], v[190:193], v[122:125], v[66:81]
	v_mfma_f32_32x32x16_bf16 v[82:97], v[206:209], v[126:129], v[82:97]
	v_mfma_f32_32x32x16_bf16 v[66:81], v[194:197], v[126:129], v[66:81]
	v_bfe_i32 v160, v185, 0, 1
	v_bfe_i32 v161, v185, 1, 1
	v_bfe_i32 v162, v185, 2, 1
	v_bfe_i32 v163, v185, 3, 1
	v_bfe_i32 v164, v185, 8, 1
	v_bfe_i32 v165, v185, 9, 1
	v_bfe_i32 v166, v185, 10, 1
	v_bfe_i32 v167, v185, 11, 1
	v_bfe_i32 v168, v185, 16, 1
	v_bfe_i32 v169, v185, 17, 1
	v_bfe_i32 v170, v185, 18, 1
	v_bfe_i32 v171, v185, 19, 1
	v_bfe_i32 v172, v185, 24, 1
	v_bfe_i32 v173, v185, 25, 1
	v_bfe_i32 v174, v185, 26, 1
	v_bfe_i32 v175, v185, 27, 1
	v_bfe_i32 v186, v0, 0, 1
	v_bfe_i32 v187, v0, 1, 1
	v_bfe_i32 v188, v0, 2, 1
	v_bfe_i32 v189, v0, 3, 1
	v_bfe_i32 v190, v0, 8, 1
	v_bfe_i32 v191, v0, 9, 1
	v_bfe_i32 v192, v0, 10, 1
	v_bfe_i32 v193, v0, 11, 1
	v_bfe_i32 v194, v0, 16, 1
	v_bfe_i32 v195, v0, 17, 1
	v_bfe_i32 v196, v0, 18, 1
	v_bfe_i32 v197, v0, 19, 1
	v_bfe_i32 v198, v0, 24, 1
	v_bfe_i32 v199, v0, 25, 1
	v_bfe_i32 v206, v0, 26, 1
	v_bfe_i32 v207, v0, 27, 1
	v_bfi_b32 v82, v160, v82, v215
	v_bfi_b32 v83, v161, v83, v215
	v_bfi_b32 v84, v162, v84, v215
	v_bfi_b32 v85, v163, v85, v215
	v_bfi_b32 v86, v164, v86, v215
	v_bfi_b32 v87, v165, v87, v215
	v_bfi_b32 v88, v166, v88, v215
	v_bfi_b32 v89, v167, v89, v215
	v_bfi_b32 v90, v168, v90, v215
	v_bfi_b32 v91, v169, v91, v215
	v_bfi_b32 v92, v170, v92, v215
	v_bfi_b32 v93, v171, v93, v215
	v_bfi_b32 v94, v172, v94, v215
	v_bfi_b32 v95, v173, v95, v215
	v_bfi_b32 v96, v174, v96, v215
	v_bfi_b32 v97, v175, v97, v215
	v_bfi_b32 v66, v186, v66, v215
	v_bfi_b32 v67, v187, v67, v215
	v_bfi_b32 v68, v188, v68, v215
	v_bfi_b32 v69, v189, v69, v215
	v_bfi_b32 v70, v190, v70, v215
	v_bfi_b32 v71, v191, v71, v215
	v_bfi_b32 v72, v192, v72, v215
	v_bfi_b32 v73, v193, v73, v215
	v_bfi_b32 v74, v194, v74, v215
	v_bfi_b32 v75, v195, v75, v215
	v_bfi_b32 v76, v196, v76, v215
	v_bfi_b32 v77, v197, v77, v215
	v_bfi_b32 v78, v198, v78, v215
	v_bfi_b32 v79, v199, v79, v215
	v_bfi_b32 v80, v206, v80, v215
	v_bfi_b32 v81, v207, v81, v215
	v_max3_f32 v160, v82, v83, v84
	v_max3_f32 v161, v85, v86, v87
	v_max3_f32 v162, v88, v89, v90
	v_max3_f32 v163, v91, v92, v93
	v_max3_f32 v164, v94, v95, v96
	v_max3_f32 v165, v97, v66, v67
	v_max3_f32 v166, v68, v69, v70
	v_max3_f32 v167, v71, v72, v73
	v_max3_f32 v168, v74, v75, v76
	v_max3_f32 v169, v77, v78, v79
	v_max3_f32 v160, v160, v161, v162
	v_max3_f32 v163, v163, v164, v165
	v_max3_f32 v166, v166, v167, v168
	v_max3_f32 v169, v169, v80, v81
	v_max3_f32 v160, v160, v163, v166
	v_max_f32_e32 v160, v160, v169
	v_mov_b32_e32 v161, v160
	s_nop 1
	v_permlane32_swap_b32_e32 v160, v161
	v_max_f32_e32 v160, v160, v161
	v_mov_b32_e32 v162, v184
	v_cmp_lt_f32_e32 vcc, v253, v160
	s_cbranch_vccz .Lm1_cfast
; __device__ __forceinline__ unsigned cvtpk(float lo, float hi) { unsigned r; asm("v_cvt_pk_bf16_f32 %0, %1, %2" : "=v"(r) : "v"(lo), "v"(hi)); return r; }
; template <bool MASKED>
; __device__ __forceinline__ void softmax_tile(f32x16& s0, f32x16& s1, float& m, float& l, float& alpha, unsigned mlo, unsigned mhi, bf16x8 (&pk)[4]) {
;     ...
;     const float mn = fmaxf(m, mx);
;     alpha = __builtin_amdgcn_exp2f(m - mn); m = mn;
;     float sum = 0.f;
; #pragma unroll
;     for (int r = 0; r < 16; ++r) {
;         float p0 = __builtin_amdgcn_exp2f(s0[r] - mn), p1 = __builtin_amdgcn_exp2f(s1[r] - mn);
;         if (MASKED) { if (s0[r] <= -1e29f) p0 = 0.f; if (s1[r] <= -1e29f) p1 = 0.f; }
;         s0[r] = p0; s1[r] = p1; sum += p0 + p1;
;     }
;     l = l * alpha + sum;
; #pragma unroll
;     for (int k2 = 0; k2 < 2; ++k2) {
;         u32x4 a, b;
;         a.x = cvtpk(s0[8 * k2 + 0], s0[8 * k2 + 1]); a.y = cvtpk(s0[8 * k2 + 2], s0[8 * k2 + 3]); a.z = cvtpk(s0[8 * k2 + 4], s0[8 * k2 + 5]); a.w = cvtpk(s0[8 * k2 + 6], s0[8 * k2 + 7]);
;         b.x = cvtpk(s1[8 * k2 + 0], s1[8 * k2 + 1]); b.y = cvtpk(s1[8 * k2 + 2], s1[8 * k2 + 3]); b.z = cvtpk(s1[8 * k2 + 4], s1[8 * k2 + 5]); b.w = cvtpk(s1[8 * k2 + 6], s1[8 * k2 + 7]);
;         pk[k2] = __builtin_bit_cast(bf16x8, a); pk[2 + k2] = __builtin_bit_cast(bf16x8, b);
;     }
	v_add_f32_e32 v161, v160, v252
	v_cndmask_b32_e32 v162, v184, v161, vcc
	v_sub_f32_e32 v161, v162, v252
	v_cndmask_b32_e32 v161, 0, v161, vcc
	v_mov_b32_e32 v160, 0x41000000
	v_cndmask_b32_e32 v253, v253, v160, vcc
	v_cndmask_b32_e32 v252, v252, v162, vcc
	v_sub_f32_e32 v0, v184, v162
	v_exp_f32_e32 v0, v0
	v_sub_f32_e32 v82, v82, v161
	v_sub_f32_e32 v83, v83, v161
	v_sub_f32_e32 v84, v84, v161
	v_sub_f32_e32 v85, v85, v161
	v_sub_f32_e32 v86, v86, v161
	v_sub_f32_e32 v87, v87, v161
	v_sub_f32_e32 v88, v88, v161
	v_sub_f32_e32 v89, v89, v161
	v_sub_f32_e32 v90, v90, v161
	v_sub_f32_e32 v91, v91, v161
	v_sub_f32_e32 v92, v92, v161
	v_sub_f32_e32 v93, v93, v161
	v_sub_f32_e32 v94, v94, v161
	v_sub_f32_e32 v95, v95, v161
	v_sub_f32_e32 v96, v96, v161
	v_sub_f32_e32 v97, v97, v161
	v_sub_f32_e32 v66, v66, v161
	v_sub_f32_e32 v67, v67, v161
	v_sub_f32_e32 v68, v68, v161
	v_sub_f32_e32 v69, v69, v161
	v_sub_f32_e32 v70, v70, v161
	v_sub_f32_e32 v71, v71, v161
	v_sub_f32_e32 v72, v72, v161
	v_sub_f32_e32 v73, v73, v161
	v_sub_f32_e32 v74, v74, v161
	v_sub_f32_e32 v75, v75, v161
	v_sub_f32_e32 v76, v76, v161
	v_sub_f32_e32 v77, v77, v161
	v_sub_f32_e32 v78, v78, v161
	v_sub_f32_e32 v79, v79, v161
	v_sub_f32_e32 v80, v80, v161
	v_sub_f32_e32 v81, v81, v161
	v_sub_f32_e32 v236, 0, v252
	v_sub_f32_e32 v237, 0, v252
	v_sub_f32_e32 v238, 0, v252
	v_sub_f32_e32 v239, 0, v252
	v_sub_f32_e32 v240, 0, v252
	v_sub_f32_e32 v241, 0, v252
	v_sub_f32_e32 v242, 0, v252
	v_sub_f32_e32 v243, 0, v252
	v_sub_f32_e32 v244, 0, v252
	v_sub_f32_e32 v245, 0, v252
	v_sub_f32_e32 v246, 0, v252
	v_sub_f32_e32 v247, 0, v252
	v_sub_f32_e32 v248, 0, v252
	v_sub_f32_e32 v249, 0, v252
	v_sub_f32_e32 v250, 0, v252
	v_sub_f32_e32 v251, 0, v252
	v_mul_f32_e32 v183, v183, v0
	v_pk_mul_f32 v[64:65], v[64:65], v[0:1] op_sel_hi:[1,0]
	v_pk_mul_f32 v[62:63], v[62:63], v[0:1] op_sel_hi:[1,0]
	v_pk_mul_f32 v[60:61], v[60:61], v[0:1] op_sel_hi:[1,0]
	v_pk_mul_f32 v[58:59], v[58:59], v[0:1] op_sel_hi:[1,0]
	v_pk_mul_f32 v[56:57], v[56:57], v[0:1] op_sel_hi:[1,0]
	v_pk_mul_f32 v[54:55], v[54:55], v[0:1] op_sel_hi:[1,0]
	v_pk_mul_f32 v[52:53], v[52:53], v[0:1] op_sel_hi:[1,0]
	v_pk_mul_f32 v[50:51], v[50:51], v[0:1] op_sel_hi:[1,0]
	v_pk_mul_f32 v[48:49], v[48:49], v[0:1] op_sel_hi:[1,0]
	v_pk_mul_f32 v[46:47], v[46:47], v[0:1] op_sel_hi:[1,0]
	v_pk_mul_f32 v[44:45], v[44:45], v[0:1] op_sel_hi:[1,0]
	v_pk_mul_f32 v[42:43], v[42:43], v[0:1] op_sel_hi:[1,0]
	v_pk_mul_f32 v[40:41], v[40:41], v[0:1] op_sel_hi:[1,0]
	v_pk_mul_f32 v[38:39], v[38:39], v[0:1] op_sel_hi:[1,0]
	v_pk_mul_f32 v[36:37], v[36:37], v[0:1] op_sel_hi:[1,0]
	v_pk_mul_f32 v[34:35], v[34:35], v[0:1] op_sel_hi:[1,0]
	v_pk_mul_f32 v[32:33], v[32:33], v[0:1] op_sel_hi:[1,0]
	v_pk_mul_f32 v[30:31], v[30:31], v[0:1] op_sel_hi:[1,0]
	v_pk_mul_f32 v[28:29], v[28:29], v[0:1] op_sel_hi:[1,0]
	v_pk_mul_f32 v[26:27], v[26:27], v[0:1] op_sel_hi:[1,0]
	v_pk_mul_f32 v[24:25], v[24:25], v[0:1] op_sel_hi:[1,0]
	v_pk_mul_f32 v[22:23], v[22:23], v[0:1] op_sel_hi:[1,0]
	v_pk_mul_f32 v[20:21], v[20:21], v[0:1] op_sel_hi:[1,0]
	v_pk_mul_f32 v[18:19], v[18:19], v[0:1] op_sel_hi:[1,0]
	v_pk_mul_f32 v[16:17], v[16:17], v[0:1] op_sel_hi:[1,0]
	v_pk_mul_f32 v[14:15], v[14:15], v[0:1] op_sel_hi:[1,0]
	v_pk_mul_f32 v[12:13], v[12:13], v[0:1] op_sel_hi:[1,0]
	v_pk_mul_f32 v[10:11], v[10:11], v[0:1] op_sel_hi:[1,0]
	v_pk_mul_f32 v[8:9], v[8:9], v[0:1] op_sel_hi:[1,0]
	v_pk_mul_f32 v[6:7], v[6:7], v[0:1] op_sel_hi:[1,0]
	v_pk_mul_f32 v[4:5], v[4:5], v[0:1] op_sel_hi:[1,0]
	v_pk_mul_f32 v[2:3], v[2:3], v[0:1] op_sel_hi:[1,0]
.Lm1_cfast:
	v_exp_f32_e32 v82, v82
	v_exp_f32_e32 v83, v83
	v_exp_f32_e32 v84, v84
	v_exp_f32_e32 v85, v85
	v_exp_f32_e32 v86, v86
	v_exp_f32_e32 v87, v87
	v_exp_f32_e32 v88, v88
	v_exp_f32_e32 v89, v89
	v_exp_f32_e32 v90, v90
	v_exp_f32_e32 v91, v91
	v_exp_f32_e32 v92, v92
	v_exp_f32_e32 v93, v93
	v_exp_f32_e32 v94, v94
	v_exp_f32_e32 v95, v95
	v_exp_f32_e32 v96, v96
	v_exp_f32_e32 v97, v97
	v_exp_f32_e32 v66, v66
	v_exp_f32_e32 v67, v67
	v_exp_f32_e32 v68, v68
	v_exp_f32_e32 v69, v69
	v_exp_f32_e32 v70, v70
	v_exp_f32_e32 v71, v71
	v_exp_f32_e32 v72, v72
	v_exp_f32_e32 v73, v73
	v_exp_f32_e32 v74, v74
	v_exp_f32_e32 v75, v75
	v_exp_f32_e32 v76, v76
	v_exp_f32_e32 v77, v77
	v_exp_f32_e32 v78, v78
	v_exp_f32_e32 v79, v79
	v_exp_f32_e32 v80, v80
	v_exp_f32_e32 v81, v81
	v_pk_add_f32 v[164:165], v[82:83], v[84:85]
	v_pk_add_f32 v[166:167], v[86:87], v[88:89]
	v_pk_add_f32 v[168:169], v[90:91], v[92:93]
	v_pk_add_f32 v[170:171], v[94:95], v[96:97]
	v_pk_add_f32 v[172:173], v[66:67], v[68:69]
	v_pk_add_f32 v[174:175], v[70:71], v[72:73]
	v_pk_add_f32 v[186:187], v[74:75], v[76:77]
	v_pk_add_f32 v[188:189], v[78:79], v[80:81]
	v_pk_add_f32 v[164:165], v[164:165], v[166:167]
	v_pk_add_f32 v[168:169], v[168:169], v[170:171]
	v_pk_add_f32 v[172:173], v[172:173], v[174:175]
	v_pk_add_f32 v[186:187], v[186:187], v[188:189]
	v_pk_add_f32 v[164:165], v[164:165], v[168:169]
	v_pk_add_f32 v[172:173], v[172:173], v[186:187]
	v_pk_add_f32 v[164:165], v[164:165], v[172:173]
	v_add_f32_e32 v164, v164, v165
	v_cvt_pk_bf16_f32 v66, v66, v67
	v_cvt_pk_bf16_f32 v67, v68, v69
	v_cvt_pk_bf16_f32 v68, v70, v71
	v_cvt_pk_bf16_f32 v69, v72, v73
	v_cvt_pk_bf16_f32 v70, v74, v75
	v_cvt_pk_bf16_f32 v71, v76, v77
	v_cvt_pk_bf16_f32 v72, v78, v79
	v_cvt_pk_bf16_f32 v73, v80, v81
	v_cvt_pk_bf16_f32 v74, v82, v83
	v_cvt_pk_bf16_f32 v75, v84, v85
	v_cvt_pk_bf16_f32 v76, v86, v87
	v_cvt_pk_bf16_f32 v77, v88, v89
	v_cvt_pk_bf16_f32 v78, v90, v91
	v_cvt_pk_bf16_f32 v79, v92, v93
	v_cvt_pk_bf16_f32 v80, v94, v95
	v_cvt_pk_bf16_f32 v81, v96, v97
	v_add_f32_e32 v164, v164, v183
	v_mov_b32_e32 v83, v164
	v_mov_b32_e32 v82, v162

; __device__ __forceinline__ float max_x32(float v) { const unsigned u = __float_as_uint(v); auto r = __builtin_amdgcn_permlane32_swap(u, u, false, false); return fmaxf(__uint_as_float(r[0]), __uint_as_float(r[1])); }
; template <bool MASKED>
; __device__ __forceinline__ void softmax_tile(f32x16& s0, f32x16& s1, float& m, float& l, float& alpha, unsigned mlo, unsigned mhi, bf16x8 (&pk)[4]) {
;     ...
;     float mx = fmaxf(s0[0], s1[0]);
; #pragma unroll
;     for (int r = 1; r < 16; ++r) mx = fmaxf(mx, fmaxf(s0[r], s1[r]));
;     mx = max_x32(mx);
;     const float mn = fmaxf(m, mx);
;     alpha = __builtin_amdgcn_exp2f(m - mn); m = mn;
.LBB0_1190:
	s_cmp_gt_i32 s14, s49
	s_cbranch_scc1 .LBB0_1194
	s_mul_i32 s15, s50, 0xa000
	s_add_i32 s15, s15, 0
	v_add_u32_e32 v0, s15, v186
	v_add_u32_e32 v6, v0, v188
	v_add_u32_e32 v14, v0, v189
	ds_read_b128 v[2:5], v6
	ds_read_b128 v[6:9], v6 offset:8192
	ds_read_b128 v[10:13], v14
	ds_read_b128 v[160:163], v14 offset:8192
	v_add_u32_e32 v14, v0, v190
	ds_read_b128 v[164:167], v14
	ds_read_b128 v[168:171], v14 offset:8192
	v_add_u32_e32 v14, v0, v191
	ds_read_b128 v[172:175], v14 offset:8192
	ds_read_b128 v[206:209], v14
	v_add_u32_e32 v14, s15, v177
	s_waitcnt lgkmcnt(0)
	v_mfma_f32_32x32x16_bf16 v[96:111], v[2:5], v[112:115], v[236:251]
	v_mfma_f32_32x32x16_bf16 v[80:95], v[6:9], v[112:115], v[236:251]
	v_mfma_f32_32x32x16_bf16 v[96:111], v[10:13], v[116:119], v[96:111]
	v_mfma_f32_32x32x16_bf16 v[80:95], v[160:163], v[116:119], v[80:95]
	v_mfma_f32_32x32x16_bf16 v[96:111], v[164:167], v[120:123], v[96:111]
	v_mfma_f32_32x32x16_bf16 v[80:95], v[168:171], v[120:123], v[80:95]
	v_mfma_f32_32x32x16_bf16 v[96:111], v[206:209], v[124:127], v[96:111]
	v_mfma_f32_32x32x16_bf16 v[80:95], v[172:175], v[124:127], v[80:95]
	v_add_u32_e32 v6, v0, v192
	v_add_u32_e32 v15, v0, v193
	ds_read_b128 v[2:5], v6
	ds_read_b128 v[6:9], v6 offset:8192
	ds_read_b128 v[10:13], v15
	ds_read_b128 v[160:163], v15 offset:8192
	v_add_u32_e32 v15, v0, v194
	v_add_u32_e32 v0, v0, v195
	ds_read_b128 v[164:167], v15
	ds_read_b128 v[168:171], v15 offset:8192
	ds_read_b128 v[172:175], v0 offset:8192
	ds_read_b128 v[206:209], v0
	s_waitcnt lgkmcnt(0)
	v_mfma_f32_32x32x16_bf16 v[96:111], v[2:5], v[128:131], v[96:111]
	v_mfma_f32_32x32x16_bf16 v[80:95], v[6:9], v[128:131], v[80:95]
	v_mfma_f32_32x32x16_bf16 v[96:111], v[10:13], v[132:135], v[96:111]
	v_mfma_f32_32x32x16_bf16 v[80:95], v[160:163], v[132:135], v[80:95]
	v_mfma_f32_32x32x16_bf16 v[96:111], v[164:167], v[136:139], v[96:111]
	v_mfma_f32_32x32x16_bf16 v[80:95], v[168:171], v[136:139], v[80:95]
	v_mfma_f32_32x32x16_bf16 v[96:111], v[206:209], v[140:143], v[96:111]
	v_mfma_f32_32x32x16_bf16 v[80:95], v[172:175], v[140:143], v[80:95]
	v_add_u32_e32 v0, v14, v196
	ds_read_b128 v[2:5], v0 offset:32768
	ds_read_b128 v[6:9], v0 offset:36864
	v_add_u32_e32 v0, v14, v197
	ds_read_b128 v[10:13], v0 offset:32768
	ds_read_b128 v[160:163], v0 offset:36864
	v_add_u32_e32 v0, v14, v198
	ds_read_b128 v[164:167], v0 offset:32768
	ds_read_b128 v[168:171], v0 offset:36864
	v_add_u32_e32 v0, v14, v199
	ds_read_b128 v[172:175], v0 offset:36864
	ds_read_b128 v[206:209], v0 offset:32768
	s_waitcnt lgkmcnt(0)
	v_mfma_f32_32x32x16_bf16 v[96:111], v[2:5], v[144:147], v[96:111]
	v_mfma_f32_32x32x16_bf16 v[80:95], v[6:9], v[144:147], v[80:95]
	v_mfma_f32_32x32x16_bf16 v[96:111], v[10:13], v[148:151], v[96:111]
	v_mfma_f32_32x32x16_bf16 v[80:95], v[160:163], v[148:151], v[80:95]
	v_mfma_f32_32x32x16_bf16 v[96:111], v[164:167], v[152:155], v[96:111]
	v_mfma_f32_32x32x16_bf16 v[80:95], v[168:171], v[152:155], v[80:95]
	v_mfma_f32_32x32x16_bf16 v[96:111], v[206:209], v[156:159], v[96:111]
	v_mfma_f32_32x32x16_bf16 v[80:95], v[172:175], v[156:159], v[80:95]
	s_nop 11
	v_max3_f32 v160, v96, v97, v98
	v_max3_f32 v161, v99, v100, v101
	v_max3_f32 v162, v102, v103, v104
	v_max3_f32 v163, v105, v106, v107
	v_max3_f32 v164, v108, v109, v110
	v_max3_f32 v165, v111, v80, v81
	v_max3_f32 v166, v82, v83, v84
	v_max3_f32 v167, v85, v86, v87
	v_max3_f32 v168, v88, v89, v90
	v_max3_f32 v169, v91, v92, v93
	v_max3_f32 v160, v160, v161, v162
	v_max3_f32 v163, v163, v164, v165
	v_max3_f32 v166, v166, v167, v168
	v_max3_f32 v169, v169, v94, v95
	v_max3_f32 v160, v160, v163, v166
	v_max_f32_e32 v160, v160, v169
	v_mov_b32_e32 v161, v160
	s_nop 1
	v_permlane32_swap_b32_e32 v160, v161
	v_max_f32_e32 v160, v160, v161
	v_mov_b32_e32 v14, v235
	v_cmp_lt_f32_e32 vcc, v253, v160
	s_cbranch_vccz .Lm0_cfast
; __device__ __forceinline__ unsigned cvtpk(float lo, float hi) { unsigned r; asm("v_cvt_pk_bf16_f32 %0, %1, %2" : "=v"(r) : "v"(lo), "v"(hi)); return r; }
; template <bool MASKED>
; __device__ __forceinline__ void softmax_tile(f32x16& s0, f32x16& s1, float& m, float& l, float& alpha, unsigned mlo, unsigned mhi, bf16x8 (&pk)[4]) {
;     ...
;     const float mn = fmaxf(m, mx);
;     alpha = __builtin_amdgcn_exp2f(m - mn); m = mn;
;     float sum = 0.f;
; #pragma unroll
;     for (int r = 0; r < 16; ++r) {
;         float p0 = __builtin_amdgcn_exp2f(s0[r] - mn), p1 = __builtin_amdgcn_exp2f(s1[r] - mn);
;         if (MASKED) { if (s0[r] <= -1e29f) p0 = 0.f; if (s1[r] <= -1e29f) p1 = 0.f; }
;         s0[r] = p0; s1[r] = p1; sum += p0 + p1;
;     }
;     l = l * alpha + sum;
; #pragma unroll
;     for (int k2 = 0; k2 < 2; ++k2) {
;         u32x4 a, b;
;         a.x = cvtpk(s0[8 * k2 + 0], s0[8 * k2 + 1]); a.y = cvtpk(s0[8 * k2 + 2], s0[8 * k2 + 3]); a.z = cvtpk(s0[8 * k2 + 4], s0[8 * k2 + 5]); a.w = cvtpk(s0[8 * k2 + 6], s0[8 * k2 + 7]);
;         b.x = cvtpk(s1[8 * k2 + 0], s1[8 * k2 + 1]); b.y = cvtpk(s1[8 * k2 + 2], s1[8 * k2 + 3]); b.z = cvtpk(s1[8 * k2 + 4], s1[8 * k2 + 5]); b.w = cvtpk(s1[8 * k2 + 6], s1[8 * k2 + 7]);
;         pk[k2] = __builtin_bit_cast(bf16x8, a); pk[2 + k2] = __builtin_bit_cast(bf16x8, b);
;     }
	v_add_f32_e32 v161, v160, v252
	v_cndmask_b32_e32 v14, v235, v161, vcc
	v_sub_f32_e32 v161, v14, v252
	v_cndmask_b32_e32 v161, 0, v161, vcc
	v_mov_b32_e32 v160, 0x41000000
	v_cndmask_b32_e32 v253, v253, v160, vcc
	v_cndmask_b32_e32 v252, v252, v14, vcc
	v_sub_f32_e32 v0, v235, v14
	v_exp_f32_e32 v0, v0
	v_sub_f32_e32 v96, v96, v161
	v_sub_f32_e32 v97, v97, v161
	v_sub_f32_e32 v98, v98, v161
	v_sub_f32_e32 v99, v99, v161
	v_sub_f32_e32 v100, v100, v161
	v_sub_f32_e32 v101, v101, v161
	v_sub_f32_e32 v102, v102, v161
	v_sub_f32_e32 v103, v103, v161
	v_sub_f32_e32 v104, v104, v161
	v_sub_f32_e32 v105, v105, v161
	v_sub_f32_e32 v106, v106, v161
	v_sub_f32_e32 v107, v107, v161
	v_sub_f32_e32 v108, v108, v161
	v_sub_f32_e32 v109, v109, v161
	v_sub_f32_e32 v110, v110, v161
	v_sub_f32_e32 v111, v111, v161
	v_sub_f32_e32 v80, v80, v161
	v_sub_f32_e32 v81, v81, v161
	v_sub_f32_e32 v82, v82, v161
	v_sub_f32_e32 v83, v83, v161
	v_sub_f32_e32 v84, v84, v161
	v_sub_f32_e32 v85, v85, v161
	v_sub_f32_e32 v86, v86, v161
	v_sub_f32_e32 v87, v87, v161
	v_sub_f32_e32 v88, v88, v161
	v_sub_f32_e32 v89, v89, v161
	v_sub_f32_e32 v90, v90, v161
	v_sub_f32_e32 v91, v91, v161
	v_sub_f32_e32 v92, v92, v161
	v_sub_f32_e32 v93, v93, v161
	v_sub_f32_e32 v94, v94, v161
	v_sub_f32_e32 v95, v95, v161
	v_sub_f32_e32 v236, 0, v252
	v_sub_f32_e32 v237, 0, v252
	v_sub_f32_e32 v238, 0, v252
	v_sub_f32_e32 v239, 0, v252
	v_sub_f32_e32 v240, 0, v252
	v_sub_f32_e32 v241, 0, v252
	v_sub_f32_e32 v242, 0, v252
	v_sub_f32_e32 v243, 0, v252
	v_sub_f32_e32 v244, 0, v252
	v_sub_f32_e32 v245, 0, v252
	v_sub_f32_e32 v246, 0, v252
	v_sub_f32_e32 v247, 0, v252
	v_sub_f32_e32 v248, 0, v252
	v_sub_f32_e32 v249, 0, v252
	v_sub_f32_e32 v250, 0, v252
	v_sub_f32_e32 v251, 0, v252
	v_mul_f32_e32 v234, v234, v0
	v_pk_mul_f32 v[78:79], v[78:79], v[0:1] op_sel_hi:[1,0]
	v_pk_mul_f32 v[76:77], v[76:77], v[0:1] op_sel_hi:[1,0]
	v_pk_mul_f32 v[74:75], v[74:75], v[0:1] op_sel_hi:[1,0]
	v_pk_mul_f32 v[72:73], v[72:73], v[0:1] op_sel_hi:[1,0]
	v_pk_mul_f32 v[70:71], v[70:71], v[0:1] op_sel_hi:[1,0]
	v_pk_mul_f32 v[68:69], v[68:69], v[0:1] op_sel_hi:[1,0]
	v_pk_mul_f32 v[66:67], v[66:67], v[0:1] op_sel_hi:[1,0]
	v_pk_mul_f32 v[64:65], v[64:65], v[0:1] op_sel_hi:[1,0]
	v_pk_mul_f32 v[62:63], v[62:63], v[0:1] op_sel_hi:[1,0]
	v_pk_mul_f32 v[60:61], v[60:61], v[0:1] op_sel_hi:[1,0]
	v_pk_mul_f32 v[58:59], v[58:59], v[0:1] op_sel_hi:[1,0]
	v_pk_mul_f32 v[56:57], v[56:57], v[0:1] op_sel_hi:[1,0]
	v_pk_mul_f32 v[54:55], v[54:55], v[0:1] op_sel_hi:[1,0]
	v_pk_mul_f32 v[52:53], v[52:53], v[0:1] op_sel_hi:[1,0]
	v_pk_mul_f32 v[50:51], v[50:51], v[0:1] op_sel_hi:[1,0]
	v_pk_mul_f32 v[48:49], v[48:49], v[0:1] op_sel_hi:[1,0]
	v_pk_mul_f32 v[46:47], v[46:47], v[0:1] op_sel_hi:[1,0]
	v_pk_mul_f32 v[44:45], v[44:45], v[0:1] op_sel_hi:[1,0]
	v_pk_mul_f32 v[42:43], v[42:43], v[0:1] op_sel_hi:[1,0]
	v_pk_mul_f32 v[40:41], v[40:41], v[0:1] op_sel_hi:[1,0]
	v_pk_mul_f32 v[38:39], v[38:39], v[0:1] op_sel_hi:[1,0]
	v_pk_mul_f32 v[36:37], v[36:37], v[0:1] op_sel_hi:[1,0]
	v_pk_mul_f32 v[34:35], v[34:35], v[0:1] op_sel_hi:[1,0]
	v_pk_mul_f32 v[32:33], v[32:33], v[0:1] op_sel_hi:[1,0]
	v_pk_mul_f32 v[30:31], v[30:31], v[0:1] op_sel_hi:[1,0]
	v_pk_mul_f32 v[28:29], v[28:29], v[0:1] op_sel_hi:[1,0]
	v_pk_mul_f32 v[26:27], v[26:27], v[0:1] op_sel_hi:[1,0]
	v_pk_mul_f32 v[24:25], v[24:25], v[0:1] op_sel_hi:[1,0]
	v_pk_mul_f32 v[22:23], v[22:23], v[0:1] op_sel_hi:[1,0]
	v_pk_mul_f32 v[20:21], v[20:21], v[0:1] op_sel_hi:[1,0]
	v_pk_mul_f32 v[18:19], v[18:19], v[0:1] op_sel_hi:[1,0]
	v_pk_mul_f32 v[16:17], v[16:17], v[0:1] op_sel_hi:[1,0]
.Lm0_cfast:
	v_exp_f32_e32 v96, v96
	v_exp_f32_e32 v97, v97
	v_exp_f32_e32 v98, v98
	v_exp_f32_e32 v99, v99
	v_exp_f32_e32 v100, v100
	v_exp_f32_e32 v101, v101
	v_exp_f32_e32 v102, v102
	v_exp_f32_e32 v103, v103
	v_exp_f32_e32 v104, v104
	v_exp_f32_e32 v105, v105
	v_exp_f32_e32 v106, v106
	v_exp_f32_e32 v107, v107
	v_exp_f32_e32 v108, v108
	v_exp_f32_e32 v109, v109
	v_exp_f32_e32 v110, v110
	v_exp_f32_e32 v111, v111
	v_exp_f32_e32 v80, v80
	v_exp_f32_e32 v81, v81
	v_exp_f32_e32 v82, v82
	v_exp_f32_e32 v83, v83
	v_exp_f32_e32 v84, v84
	v_exp_f32_e32 v85, v85
	v_exp_f32_e32 v86, v86
	v_exp_f32_e32 v87, v87
	v_exp_f32_e32 v88, v88
	v_exp_f32_e32 v89, v89
	v_exp_f32_e32 v90, v90
	v_exp_f32_e32 v91, v91
	v_exp_f32_e32 v92, v92
	v_exp_f32_e32 v93, v93
	v_exp_f32_e32 v94, v94
	v_exp_f32_e32 v95, v95
	v_pk_add_f32 v[160:161], v[96:97], v[98:99]
	v_pk_add_f32 v[162:163], v[100:101], v[102:103]
	v_pk_add_f32 v[164:165], v[104:105], v[106:107]
	v_pk_add_f32 v[166:167], v[108:109], v[110:111]
	v_pk_add_f32 v[168:169], v[80:81], v[82:83]
	v_pk_add_f32 v[170:171], v[84:85], v[86:87]
	v_pk_add_f32 v[172:173], v[88:89], v[90:91]
	v_pk_add_f32 v[174:175], v[92:93], v[94:95]
	v_pk_add_f32 v[160:161], v[160:161], v[162:163]
	v_pk_add_f32 v[164:165], v[164:165], v[166:167]
	v_pk_add_f32 v[168:169], v[168:169], v[170:171]
	v_pk_add_f32 v[172:173], v[172:173], v[174:175]
	v_pk_add_f32 v[160:161], v[160:161], v[164:165]
	v_pk_add_f32 v[168:169], v[168:169], v[172:173]
	v_pk_add_f32 v[160:161], v[160:161], v[168:169]
	v_add_f32_e32 v15, v160, v161
	v_cvt_pk_bf16_f32 v2, v80, v81
	v_cvt_pk_bf16_f32 v3, v82, v83
	v_cvt_pk_bf16_f32 v4, v84, v85
	v_cvt_pk_bf16_f32 v5, v86, v87
	v_cvt_pk_bf16_f32 v6, v88, v89
	v_cvt_pk_bf16_f32 v7, v90, v91
	v_cvt_pk_bf16_f32 v8, v92, v93
	v_cvt_pk_bf16_f32 v9, v94, v95
	v_cvt_pk_bf16_f32 v80, v104, v105
	v_cvt_pk_bf16_f32 v81, v106, v107
	v_cvt_pk_bf16_f32 v82, v108, v109
	v_cvt_pk_bf16_f32 v83, v110, v111
	v_cvt_pk_bf16_f32 v10, v96, v97
	v_cvt_pk_bf16_f32 v11, v98, v99
	v_cvt_pk_bf16_f32 v12, v100, v101
	v_cvt_pk_bf16_f32 v13, v102, v103
	v_add_f32_e32 v15, v15, v234
